# gdn unit final stage hand-written: batched LDS fragment reads, transposed Qeff/M products with wide stores
# speedup vs baseline: 1.0080x; 1.0047x over previous
; __device__ __forceinline__ float bf2f(bf16_t b) { return __uint_as_float((unsigned)b << 16); }
; __device__ __forceinline__ bf16_t f2bf(float f) { return (bf16_t)(pk2(f, 0.f) & 0xffffu); }
; __device__ __forceinline__ float fexp(float x) { return __expf(x); }
; __device__ __forceinline__ void gdn_unit(const Ctx& X, LAS unsigned char* hl, int b, int c, int h, int tid_h, int w4, int lane, int layer) {
;     ...
;     {
;         f32x4 acc[4];
;         const float eG63 = fexp(Gs[63]);
; #pragma unroll
;         for (int ct = 0; ct < 4; ++ct) acc[ct] = mma16(P, 16 * w4, WT, 16 * ct, (f32x4){0.f, 0.f, 0.f, 0.f}, r, q);
;         bf16_t* qe = WSP(bf16_t, WS_QEFF) + (size_t)uid * 4096;
; #pragma unroll
;         for (int ct = 0; ct < 4; ++ct)
; #pragma unroll
;             for (int j = 0; j < 4; ++j) { const int ii = 16 * w4 + 4 * q + j, col = 16 * ct + r;
;                 qe[ii * 64 + col] = f2bf(bf2f(Q[ii * LT + col]) * fexp(Gs[ii]) - acc[ct][j]); }
; #pragma unroll
;         for (int ct = 0; ct < 4; ++ct) acc[ct] = mma16(P, 16 * w4, UT, 16 * ct, (f32x4){0.f, 0.f, 0.f, 0.f}, r, q);
;         store_oloc(WSP(bf16_t, WS_OLOC), uid, w4, lane, acc);
; #pragma unroll
;         for (int ct = 0; ct < 4; ++ct) acc[ct] = mma16(KDT, 16 * w4, WT, 16 * ct, (f32x4){0.f, 0.f, 0.f, 0.f}, r, q);
;         bf16_t* mm = WSP(bf16_t, WS_MM) + (size_t)(uid - 2048) * 4096;
; #pragma unroll
;         for (int ct = 0; ct < 4; ++ct)
; #pragma unroll
;             for (int j = 0; j < 4; ++j) { const int ii = 16 * w4 + 4 * q + j, col = 16 * ct + r;
;                 mm[((w4 * 2 + (ct >> 1)) * 64 + (r >> 2) * 16 + 4 * q + j) * 8 + (ct & 1) * 4 + (r & 3)] = f2bf((ii == col ? eG63 : 0.f) - acc[ct][j]); }
; #pragma unroll
;         for (int ct = 0; ct < 4; ++ct) acc[ct] = mma16(KDT, 16 * w4, UT, 16 * ct, (f32x4){0.f, 0.f, 0.f, 0.f}, r, q);
;         store_bc(WSP(bf16_t, WS_BCS), uid, w4, r, q, acc);
;     }
.LBB0_619:
	s_waitcnt lgkmcnt(0)
	s_barrier
	v_bfe_u32 v54, v224, 6, 2
	v_and_b32_e32 v55, 15, v232
	v_lshrrev_b32_e32 v56, 4, v232
	v_lshl_or_b32 v57, v54, 4, v55
	v_mul_u32_u24_e32 v58, 0x90, v57
	v_mul_u32_u24_e32 v59, 0x90, v55
	v_lshl_add_u32 v60, v56, 4, v58
	v_lshl_add_u32 v61, v56, 4, v59
	v_add_u32_e32 v60, v182, v60
	v_add_u32_e32 v61, v182, v61
	v_add_u32_e32 v178, 0xb400, v60
	v_add_u32_e32 v179, 0x4800, v61
	v_add_u32_e32 v60, 0x9000, v60
	v_add_u32_e32 v61, 0x6c00, v61
	ds_read_b128 v[6:9], v178
	ds_read_b128 v[10:13], v178 offset:64
	ds_read_b128 v[22:25], v179
	ds_read_b128 v[26:29], v179 offset:64
	ds_read_b128 v[30:33], v179 offset:2304
	ds_read_b128 v[34:37], v179 offset:2368
	ds_read_b128 v[38:41], v179 offset:4608
	ds_read_b128 v[42:45], v179 offset:4672
	ds_read_b128 v[46:49], v179 offset:6912
	ds_read_b128 v[50:53], v179 offset:6976
	ds_read_b128 v[14:17], v60
	ds_read_b128 v[18:21], v60 offset:64
	v_lshl_add_u32 v62, v57, 2, v185
	v_lshl_add_u32 v63, v56, 3, v58
	v_add_u32_e32 v63, v182, v63
	ds_read_b32 v176, v62
	ds_read_b32 v177, v185 offset:252
	s_lshl_b32 s0, s22, 9
	s_lshl_b32 s1, s23, 7
	s_add_i32 s1, s1, s0
	s_or_b32 s0, s1, s21
	s_ashr_i32 s1, s0, 31
	s_lshl_b64 s[0:1], s[0:1], 13
	s_add_u32 s4, s89, s0
	s_addc_u32 s5, s78, s1
	s_add_u32 s6, s79, s0
	s_addc_u32 s7, s80, s1
	v_readlane_b32 s98, v253, 3
	v_readlane_b32 s99, v253, 4
	s_add_u32 s98, s98, s0
	s_addc_u32 s99, s99, s1
	s_add_u32 s98, s98, 0xff000000
	s_addc_u32 s99, s99, -1
	s_add_u32 s100, s74, s0
	s_addc_u32 s101, s75, s1
	v_readfirstlane_b32 s32, v54
	v_lshlrev_b32_e32 v64, 11, v54
	v_lshlrev_b32_e32 v65, 5, v232
	v_lshl_add_u32 v64, v232, 4, v64
	v_lshlrev_b32_e32 v66, 9, v54
	v_lshl_add_u32 v66, v232, 3, v66
	v_add_u32_e32 v67, 0x1000, v66
	v_lshlrev_b32_e32 v71, 7, v57
	v_lshl_add_u32 v71, v56, 3, v71
	v_lshlrev_b32_e32 v70, 2, v56
	v_sub_u32_e32 v70, v55, v70
	s_waitcnt lgkmcnt(4)
	v_mfma_f32_16x16x32_bf16 v[134:137], v[22:25], v[6:9], 0
	v_mfma_f32_16x16x32_bf16 v[138:141], v[30:33], v[6:9], 0
	v_mfma_f32_16x16x32_bf16 v[142:145], v[38:41], v[6:9], 0
	v_mfma_f32_16x16x32_bf16 v[146:149], v[46:49], v[6:9], 0
	v_mfma_f32_16x16x32_bf16 v[134:137], v[26:29], v[10:13], v[134:137]
	v_mfma_f32_16x16x32_bf16 v[138:141], v[34:37], v[10:13], v[138:141]
	v_mfma_f32_16x16x32_bf16 v[142:145], v[42:45], v[10:13], v[142:145]
	v_mfma_f32_16x16x32_bf16 v[146:149], v[50:53], v[10:13], v[146:149]
	ds_read_b64 v[150:151], v63
	ds_read_b64 v[152:153], v63 offset:32
	ds_read_b64 v[172:173], v63 offset:64
	ds_read_b64 v[174:175], v63 offset:96
	ds_read_b128 v[186:189], v61
	ds_read_b128 v[190:193], v61 offset:64
	ds_read_b128 v[194:197], v61 offset:2304
	ds_read_b128 v[198:201], v61 offset:2368
	ds_read_b128 v[202:205], v61 offset:4608
	ds_read_b128 v[206:209], v61 offset:4672
	ds_read_b128 v[210:213], v61 offset:6912
	s_waitcnt lgkmcnt(13)
	v_mfma_f32_16x16x32_bf16 v[236:239], v[22:25], v[14:17], 0
	v_mfma_f32_16x16x32_bf16 v[240:243], v[30:33], v[14:17], 0
	v_mfma_f32_16x16x32_bf16 v[244:247], v[38:41], v[14:17], 0
	v_mfma_f32_16x16x32_bf16 v[248:251], v[46:49], v[14:17], 0
	v_mfma_f32_16x16x32_bf16 v[236:239], v[26:29], v[18:21], v[236:239]
	v_mfma_f32_16x16x32_bf16 v[240:243], v[34:37], v[18:21], v[240:243]
	v_mfma_f32_16x16x32_bf16 v[244:247], v[42:45], v[18:21], v[244:247]
	v_mfma_f32_16x16x32_bf16 v[248:251], v[50:53], v[18:21], v[248:251]
	ds_read_b128 v[214:217], v61 offset:6976
	s_waitcnt lgkmcnt(8)
	v_mul_f32_e32 v176, 0x3fb8aa3b, v176
	v_mul_f32_e32 v177, 0x3fb8aa3b, v177
	v_exp_f32_e32 v176, v176
	v_exp_f32_e32 v177, v177
	v_cmp_eq_u32_e32 vcc, 0, v70
	v_cmp_eq_u32_e64 s[0:1], 1, v70
	v_cmp_eq_u32_e64 s[82:83], 2, v70
	v_cmp_eq_u32_e64 s[94:95], 3, v70
	s_waitcnt lgkmcnt(0)
; __device__ __forceinline__ float bf2f(bf16_t b) { return __uint_as_float((unsigned)b << 16); }
; __device__ __forceinline__ bf16_t f2bf(float f) { return (bf16_t)(pk2(f, 0.f) & 0xffffu); }
; __device__ __forceinline__ float fexp(float x) { return __expf(x); }
; #define LBAR() do { asm volatile("s_waitcnt lgkmcnt(0)" ::: "memory"); __builtin_amdgcn_s_barrier(); asm volatile("" ::: "memory"); } while (0)
; __device__ __forceinline__ void gdn_unit(const Ctx& X, LAS unsigned char* hl, int b, int c, int h, int tid_h, int w4, int lane, int layer) {
;     ...
;     {
;         f32x4 acc[4];
;         const float eG63 = fexp(Gs[63]);
; #pragma unroll
;         for (int ct = 0; ct < 4; ++ct) acc[ct] = mma16(P, 16 * w4, WT, 16 * ct, (f32x4){0.f, 0.f, 0.f, 0.f}, r, q);
;         bf16_t* qe = WSP(bf16_t, WS_QEFF) + (size_t)uid * 4096;
; #pragma unroll
;         for (int ct = 0; ct < 4; ++ct)
; #pragma unroll
;             for (int j = 0; j < 4; ++j) { const int ii = 16 * w4 + 4 * q + j, col = 16 * ct + r;
;                 qe[ii * 64 + col] = f2bf(bf2f(Q[ii * LT + col]) * fexp(Gs[ii]) - acc[ct][j]); }
; #pragma unroll
;         for (int ct = 0; ct < 4; ++ct) acc[ct] = mma16(P, 16 * w4, UT, 16 * ct, (f32x4){0.f, 0.f, 0.f, 0.f}, r, q);
;         store_oloc(WSP(bf16_t, WS_OLOC), uid, w4, lane, acc);
; #pragma unroll
;         for (int ct = 0; ct < 4; ++ct) acc[ct] = mma16(KDT, 16 * w4, WT, 16 * ct, (f32x4){0.f, 0.f, 0.f, 0.f}, r, q);
;         bf16_t* mm = WSP(bf16_t, WS_MM) + (size_t)(uid - 2048) * 4096;
; #pragma unroll
;         for (int ct = 0; ct < 4; ++ct)
; #pragma unroll
;             for (int j = 0; j < 4; ++j) { const int ii = 16 * w4 + 4 * q + j, col = 16 * ct + r;
;                 mm[((w4 * 2 + (ct >> 1)) * 64 + (r >> 2) * 16 + 4 * q + j) * 8 + (ct & 1) * 4 + (r & 3)] = f2bf((ii == col ? eG63 : 0.f) - acc[ct][j]); }
; #pragma unroll
;         for (int ct = 0; ct < 4; ++ct) acc[ct] = mma16(KDT, 16 * w4, UT, 16 * ct, (f32x4){0.f, 0.f, 0.f, 0.f}, r, q);
;         store_bc(WSP(bf16_t, WS_BCS), uid, w4, r, q, acc);
;     }
;     LBAR();
	v_mfma_f32_16x16x32_bf16 v[84:87], v[6:9], v[186:189], 0
	v_mfma_f32_16x16x32_bf16 v[88:91], v[6:9], v[194:197], 0
	v_mfma_f32_16x16x32_bf16 v[92:95], v[6:9], v[202:205], 0
	v_mfma_f32_16x16x32_bf16 v[96:99], v[6:9], v[210:213], 0
	v_mfma_f32_16x16x32_bf16 v[114:117], v[14:17], v[186:189], 0
	v_mfma_f32_16x16x32_bf16 v[118:121], v[14:17], v[194:197], 0
	v_mfma_f32_16x16x32_bf16 v[122:125], v[14:17], v[202:205], 0
	v_mfma_f32_16x16x32_bf16 v[126:129], v[14:17], v[210:213], 0
	v_mfma_f32_16x16x32_bf16 v[84:87], v[10:13], v[190:193], v[84:87]
	v_mfma_f32_16x16x32_bf16 v[88:91], v[10:13], v[198:201], v[88:91]
	v_mfma_f32_16x16x32_bf16 v[92:95], v[10:13], v[206:209], v[92:95]
	v_mfma_f32_16x16x32_bf16 v[96:99], v[10:13], v[214:217], v[96:99]
	v_mfma_f32_16x16x32_bf16 v[114:117], v[18:21], v[190:193], v[114:117]
	v_mfma_f32_16x16x32_bf16 v[118:121], v[18:21], v[198:201], v[118:121]
	v_mfma_f32_16x16x32_bf16 v[122:125], v[18:21], v[206:209], v[122:125]
	v_mfma_f32_16x16x32_bf16 v[126:129], v[18:21], v[214:217], v[126:129]
	v_cndmask_b32_e32 v72, 0, v177, vcc
	v_cndmask_b32_e64 v73, 0, v177, s[0:1]
	v_cndmask_b32_e64 v74, 0, v177, s[82:83]
	v_cndmask_b32_e64 v75, 0, v177, s[94:95]
	v_lshlrev_b32_e32 v76, 16, v150
	v_and_b32_e32 v77, 0xffff0000, v150
	v_lshlrev_b32_e32 v78, 16, v151
	v_and_b32_e32 v79, 0xffff0000, v151
	v_fma_f32 v76, v176, v76, -v134
	v_fma_f32 v77, v176, v77, -v135
	v_fma_f32 v78, v176, v78, -v136
	v_fma_f32 v79, v176, v79, -v137
	v_cvt_pk_bf16_f32 v218, v76, v77
	v_cvt_pk_bf16_f32 v219, v78, v79
	global_store_dwordx2 v71, v[218:219], s[4:5]
	v_lshlrev_b32_e32 v76, 16, v152
	v_and_b32_e32 v77, 0xffff0000, v152
	v_lshlrev_b32_e32 v78, 16, v153
	v_and_b32_e32 v79, 0xffff0000, v153
	v_fma_f32 v76, v176, v76, -v138
	v_fma_f32 v77, v176, v77, -v139
	v_fma_f32 v78, v176, v78, -v140
	v_fma_f32 v79, v176, v79, -v141
	v_cvt_pk_bf16_f32 v220, v76, v77
	v_cvt_pk_bf16_f32 v221, v78, v79
	global_store_dwordx2 v71, v[220:221], s[4:5] offset:32
	v_lshlrev_b32_e32 v76, 16, v172
	v_and_b32_e32 v77, 0xffff0000, v172
	v_lshlrev_b32_e32 v78, 16, v173
	v_and_b32_e32 v79, 0xffff0000, v173
	v_fma_f32 v76, v176, v76, -v142
	v_fma_f32 v77, v176, v77, -v143
	v_fma_f32 v78, v176, v78, -v144
	v_fma_f32 v79, v176, v79, -v145
	v_cvt_pk_bf16_f32 v222, v76, v77
	v_cvt_pk_bf16_f32 v223, v78, v79
	global_store_dwordx2 v71, v[222:223], s[4:5] offset:64
	v_lshlrev_b32_e32 v76, 16, v174
	v_and_b32_e32 v77, 0xffff0000, v174
	v_lshlrev_b32_e32 v78, 16, v175
	v_and_b32_e32 v79, 0xffff0000, v175
	v_fma_f32 v76, v176, v76, -v146
	v_fma_f32 v77, v176, v77, -v147
	v_fma_f32 v78, v176, v78, -v148
	v_fma_f32 v79, v176, v79, -v149
	v_cvt_pk_bf16_f32 v226, v76, v77
	v_cvt_pk_bf16_f32 v227, v78, v79
	global_store_dwordx2 v71, v[226:227], s[4:5] offset:96
	s_cmp_eq_u32 s32, 0
	s_cselect_b32 s0, 1.0, 0
	v_fma_f32 v76, v72, s0, -v236
	v_fma_f32 v77, v73, s0, -v237
	v_fma_f32 v78, v74, s0, -v238
	v_fma_f32 v79, v75, s0, -v239
	v_cvt_pk_bf16_f32 v100, v76, v77
	v_cvt_pk_bf16_f32 v101, v78, v79
	s_cmp_eq_u32 s32, 1
	s_cselect_b32 s0, 1.0, 0
	v_fma_f32 v76, v72, s0, -v240
	v_fma_f32 v77, v73, s0, -v241
	v_fma_f32 v78, v74, s0, -v242
	v_fma_f32 v79, v75, s0, -v243
	v_cvt_pk_bf16_f32 v102, v76, v77
	v_cvt_pk_bf16_f32 v103, v78, v79
	global_store_dwordx4 v64, v[100:103], s[98:99]
	s_cmp_eq_u32 s32, 2
	s_cselect_b32 s0, 1.0, 0
	v_fma_f32 v76, v72, s0, -v244
	v_fma_f32 v77, v73, s0, -v245
	v_fma_f32 v78, v74, s0, -v246
	v_fma_f32 v79, v75, s0, -v247
	v_cvt_pk_bf16_f32 v104, v76, v77
	v_cvt_pk_bf16_f32 v105, v78, v79
	s_cmp_eq_u32 s32, 3
	s_cselect_b32 s0, 1.0, 0
	v_fma_f32 v76, v72, s0, -v248
	v_fma_f32 v77, v73, s0, -v249
	v_fma_f32 v78, v74, s0, -v250
	v_fma_f32 v79, v75, s0, -v251
	v_cvt_pk_bf16_f32 v106, v76, v77
	v_cvt_pk_bf16_f32 v107, v78, v79
	global_store_dwordx4 v64, v[104:107], s[98:99] offset:1024
	v_cvt_pk_bf16_f32 v108, v84, v85
	v_cvt_pk_bf16_f32 v109, v86, v87
	v_cvt_pk_bf16_f32 v110, v88, v89
	v_cvt_pk_bf16_f32 v111, v90, v91
	global_store_dwordx4 v65, v[108:111], s[6:7] nt
	v_cvt_pk_bf16_f32 v80, v92, v93
	v_cvt_pk_bf16_f32 v81, v94, v95
	v_cvt_pk_bf16_f32 v82, v96, v97
	v_cvt_pk_bf16_f32 v83, v98, v99
	global_store_dwordx4 v65, v[80:83], s[6:7] offset:16 nt
	v_cvt_pk_bf16_f32 v40, v114, v115
	v_cvt_pk_bf16_f32 v41, v116, v117
	global_store_dwordx2 v66, v[40:41], s[100:101]
	v_cvt_pk_bf16_f32 v42, v118, v119
	v_cvt_pk_bf16_f32 v43, v120, v121
	global_store_dwordx2 v66, v[42:43], s[100:101] offset:2048
	v_cvt_pk_bf16_f32 v44, v122, v123
	v_cvt_pk_bf16_f32 v45, v124, v125
	global_store_dwordx2 v67, v[44:45], s[100:101]
	v_cvt_pk_bf16_f32 v46, v126, v127
	v_cvt_pk_bf16_f32 v47, v128, v129
	global_store_dwordx2 v67, v[46:47], s[100:101] offset:2048
	s_waitcnt lgkmcnt(0)
	s_barrier
	s_mov_b64 s[0:1], 0
